# MLA loop: next-tile LDS staging placed inside the PV block (after the second key slice), waits recounted
# baseline (speedup 1.0000x reference)
; #define LAS __attribute__((address_space(3)))
; #define MFMA32(a, b, c) __builtin_amdgcn_mfma_f32_32x32x16_bf16((a), (b), (c), 0, 0, 0)
;     ...
;                 for (int ks = 0; ks < 4; ++ks) pf[mp][ks] = pack_frag(p[ks >> 1], ks & 1);
;             }
;             const LAS unsigned char* vb = bb + KB + r32 * VP + 8 * hi;
; #pragma unroll
;             for (int dh = 0; dh < 2; ++dh) {
;                 bf16x8 vf[4];
; #pragma unroll
;                 for (int ks = 0; ks < 4; ++ks) {
;                     const u32x2 v0 = *(const LAS u32x2*)(vb + dh * 32 * VP + 32 * ks), v1 = *(const LAS u32x2*)(vb + dh * 32 * VP + 32 * ks + 16);
;                     const u32x4 vv = {v0.x, v0.y, v1.x, v1.y}; vf[ks] = __builtin_bit_cast(bf16x8, vv); }
;                 __builtin_amdgcn_sched_barrier(0);
; #pragma unroll
;                 for (int ks = 0; ks < 4; ++ks)
; #pragma unroll
;                     for (int mp = 0; mp < NM; ++mp) o[mp][dh] = MFMA32(vf[ks], pf[mp][ks], o[mp][dh]);
;                 __builtin_amdgcn_sched_barrier(0);
;             }
;             if constexpr (MODE == 0) {
;                 const u32x4 o1 = {0x3f803f80u, 0x3f803f80u, 0x3f803f80u, 0x3f803f80u}; const bf16x8 ones = __builtin_bit_cast(bf16x8, o1);
; #pragma unroll
;                 for (int ks = 0; ks < 4; ++ks) lsum = MFMA32(ones, pf[0][ks], lsum);
;             }
;         }
;         if (it + 1 < NT) ATT_STORE((it + 1) & 1);
.LBB0_267:
	v_exp_f32_e32 v68, v68
	v_exp_f32_e32 v69, v69
	v_exp_f32_e32 v70, v70
	v_exp_f32_e32 v71, v71
	v_exp_f32_e32 v72, v72
	v_exp_f32_e32 v73, v73
	v_exp_f32_e32 v74, v74
	v_exp_f32_e32 v75, v75
	v_cvt_pk_bf16_f32 v68, v68, v69
	v_cvt_pk_bf16_f32 v69, v70, v71
	v_cvt_pk_bf16_f32 v70, v72, v73
	v_cvt_pk_bf16_f32 v71, v74, v75
	s_mov_b32 s70, s68
	s_mov_b32 s71, s68
	s_mov_b32 s69, s68
	v_mov_b64_e32 v[178:179], s[70:71]
	v_mov_b64_e32 v[176:177], s[68:69]
	v_mov_b32_e32 v208, v136
	s_waitcnt lgkmcnt(12)
	v_mfma_f32_32x32x16_bf16 v[4:19], v[144:147], v[68:71], v[4:19]
	v_exp_f32_e32 v76, v76
	v_exp_f32_e32 v77, v77
	v_exp_f32_e32 v78, v78
	v_mfma_f32_32x32x16_bf16 v[20:35], v[160:163], v[68:71], v[20:35]
	v_exp_f32_e32 v79, v79
	v_exp_f32_e32 v80, v80
	v_exp_f32_e32 v81, v81
	v_mfma_f32_32x32x16_bf16 v[36:51], v[176:179], v[68:71], v[36:51]
	v_exp_f32_e32 v82, v82
	v_exp_f32_e32 v83, v83
	v_cvt_pk_bf16_f32 v72, v76, v77
	v_cvt_pk_bf16_f32 v73, v78, v79
	v_cvt_pk_bf16_f32 v74, v80, v81
	v_cvt_pk_bf16_f32 v75, v82, v83
	s_waitcnt lgkmcnt(8)
	s_nop 0
	v_mfma_f32_32x32x16_bf16 v[4:19], v[148:151], v[72:75], v[4:19]
	v_exp_f32_e32 v84, v84
	v_exp_f32_e32 v85, v85
	v_exp_f32_e32 v86, v86
	v_mfma_f32_32x32x16_bf16 v[20:35], v[164:167], v[72:75], v[20:35]
	v_exp_f32_e32 v87, v87
	v_exp_f32_e32 v88, v88
	v_exp_f32_e32 v89, v89
	v_mfma_f32_32x32x16_bf16 v[36:51], v[176:179], v[72:75], v[36:51]
	v_exp_f32_e32 v90, v90
	v_exp_f32_e32 v91, v91
	v_cvt_pk_bf16_f32 v76, v84, v85
	v_cvt_pk_bf16_f32 v77, v86, v87
	v_cvt_pk_bf16_f32 v78, v88, v89
	v_cvt_pk_bf16_f32 v79, v90, v91
	s_bitcmp1_b32 s12, 0
	s_cselect_b32 s12, 0x5700, 0
	s_addk_i32 s12, 0x100
	v_add3_u32 v180, s12, v200, v201
	s_waitcnt vmcnt(0)
	ds_write_b128 v180, v[132:135]
	s_and_saveexec_b64 s[46:47], s[44:45]
	v_add3_u32 v180, s12, v203, v202
	ds_write_b128 v180, v[100:103] offset:128
	s_or_b64 exec, exec, s[46:47]
	s_mov_b64 s[18:19], 0x1000
	v_add_u32_e32 v180, s12, v210
	v_lshl_add_u64 v[194:195], v[194:195], 0, s[18:19]
	s_mov_b64 s[18:19], 0x10000
	v_add3_u32 v180, v180, v201, s13
	v_lshl_add_u64 v[0:1], v[0:1], 0, s[18:19]
	v_lshl_add_u64 v[196:197], v[196:197], 0, s[8:9]
	ds_write2_b64 v180, v[128:129], v[130:131] offset1:1
	s_waitcnt lgkmcnt(6)
	s_nop 0
	v_mfma_f32_32x32x16_bf16 v[4:19], v[152:155], v[76:79], v[4:19]
	v_exp_f32_e32 v92, v92
	v_exp_f32_e32 v93, v93
	v_exp_f32_e32 v94, v94
	v_mfma_f32_32x32x16_bf16 v[20:35], v[168:171], v[76:79], v[20:35]
	v_exp_f32_e32 v95, v95
	v_exp_f32_e32 v96, v96
	v_exp_f32_e32 v97, v97
	v_mfma_f32_32x32x16_bf16 v[36:51], v[176:179], v[76:79], v[36:51]
	v_exp_f32_e32 v98, v98
	v_exp_f32_e32 v99, v99
	v_cvt_pk_bf16_f32 v80, v92, v93
	v_cvt_pk_bf16_f32 v81, v94, v95
	v_cvt_pk_bf16_f32 v82, v96, v97
	v_cvt_pk_bf16_f32 v83, v98, v99
	s_waitcnt lgkmcnt(2)
	s_nop 0
	v_mfma_f32_32x32x16_bf16 v[4:19], v[156:159], v[80:83], v[4:19]
	v_mfma_f32_32x32x16_bf16 v[20:35], v[172:175], v[80:83], v[20:35]
	v_mfma_f32_32x32x16_bf16 v[36:51], v[176:179], v[80:83], v[36:51]
	s_cmp_lg_u32 s5, s11
	s_branch .Lmla_join
